# v54 with unreachable replaced code deleted (old colmax pass, old convert loops, old P5 copy loops); same executed instructions
# baseline (speedup 1.0000x reference)
.LBB0_13:
.Lcolmax_next:
.LBB0_14:
.LBB0_18:
.LBB0_20:
.LBB0_22:
.LBB0_24:
.LBB0_25:
.LBB0_27:
.LBB0_29:
.LBB0_30:
.LBB0_32:
.LBB0_34:
.LBB0_36:
.LBB0_39:
.LBB0_40:
.LBB0_43:
.LBB0_44:
.LBB0_46:
.LBB0_47:
.LBB0_50:
.LBB0_51:
.LBB0_52:
.LBB0_54:
.LBB0_57:
.LBB0_58:
.LBB0_60:
.LBB0_61:
.LBB0_63:
.LBB0_64:
.LBB0_67:
.LBB0_68:
.LBB0_71:
.LBB0_74:
.LBB0_75:
.LBB0_77:
.LBB0_78:
.LBB0_80:
.LBB0_81:
.LBB0_82:
.LBB0_83:
.LBB0_85:
.LBB0_87:
.LBB0_88:
.Lp0_after_colmax:
	v_readlane_b32 s0, v254, 15
	s_lshl_b32 s21, s0, 9
	s_mov_b32 s14, s90
	s_cmpk_gt_i32 s90, 0x69ff
	s_waitcnt lgkmcnt(0)
	s_barrier
	s_cbranch_scc1 .LBB0_115
	v_mbcnt_lo_u32_b32 v135, -1, 0
	v_mbcnt_hi_u32_b32 v135, -1, v135
	v_lshrrev_b32_e32 v136, 2, v135
	v_and_b32_e32 v137, 3, v135
	v_lshlrev_b32_e32 v230, 4, v137
	v_lshlrev_b32_e32 v231, 15, v137
	v_lshl_add_u32 v231, v136, 3, v231
	v_readlane_b32 s62, v254, 17
	v_readlane_b32 s1, v254, 16
	v_readlane_b32 s72, v254, 15
	s_mov_b32 s74, 0x42fe0000
	s_mov_b32 s11, 0
	v_lshlrev_b32_e32 v139, 11, v137
	v_lshl_add_u32 v139, v136, 2, v139
	s_nop 1
	v_add_u32_e32 v139, s62, v139
	v_lshlrev_b32_e32 v174, 2, v135
	v_xor_b32_e32 v192, 0x10, v174
	v_xor_b32_e32 v193, 0x20, v174
	v_xor_b32_e32 v194, 0x40, v174
	v_xor_b32_e32 v195, 0x80, v174
	v_lshrrev_b32_e32 v175, 5, v135
	v_and_b32_e32 v176, 31, v135
	v_lshlrev_b32_e32 v212, 9, v175
	v_lshl_add_u32 v212, v176, 4, v212
	v_add_u32_e32 v212, s62, v212
	v_lshlrev_b32_e32 v213, 12, v175
	v_lshl_add_u32 v213, v176, 4, v213
	v_readlane_b32 s48, v255, 47
	v_readlane_b32 s49, v255, 48
	v_mul_u32_u24_e32 v138, 0x20000, v136
	v_lshl_add_u32 v138, v137, 4, v138
	s_mul_i32 s3, s1, 0x1000000
	s_nop 1
	s_add_u32 s48, s48, s3
	s_addc_u32 s49, s49, 0
	s_mov_b32 s0, s72
	s_cmp_ge_u32 s0, 0x200
	s_cbranch_scc1 .Lc16_gates_done
	s_lshl_b32 s3, s0, 6
	s_add_u32 s56, s48, s3
	s_addc_u32 s57, s49, 0
	global_load_dwordx4 v[6:9], v138, s[56:57]
	s_add_u32 s56, s56, 0x8000
	s_addc_u32 s57, s57, 0
	global_load_dwordx4 v[10:13], v138, s[56:57]
	s_add_u32 s56, s56, 0x8000
	s_addc_u32 s57, s57, 0
	global_load_dwordx4 v[14:17], v138, s[56:57]
	s_add_u32 s56, s56, 0x8000
	s_addc_u32 s57, s57, 0
	global_load_dwordx4 v[18:21], v138, s[56:57]
	s_add_u32 s56, s56, 0x1e8000
	s_addc_u32 s57, s57, 0
	global_load_dwordx4 v[22:25], v138, s[56:57]
	s_add_u32 s56, s56, 0x8000
	s_addc_u32 s57, s57, 0
	global_load_dwordx4 v[26:29], v138, s[56:57]
	s_add_u32 s56, s56, 0x8000
	s_addc_u32 s57, s57, 0
	global_load_dwordx4 v[30:33], v138, s[56:57]
	s_add_u32 s56, s56, 0x8000
	s_addc_u32 s57, s57, 0
	global_load_dwordx4 v[34:37], v138, s[56:57]
	s_add_u32 s56, s56, 0x1e8000
	s_addc_u32 s57, s57, 0
	global_load_dwordx4 v[38:41], v138, s[56:57]
	s_add_u32 s56, s56, 0x8000
	s_addc_u32 s57, s57, 0
	global_load_dwordx4 v[42:45], v138, s[56:57]
	s_add_u32 s56, s56, 0x8000
	s_addc_u32 s57, s57, 0
	global_load_dwordx4 v[46:49], v138, s[56:57]
	s_add_u32 s56, s56, 0x8000
	s_addc_u32 s57, s57, 0
	global_load_dwordx4 v[50:53], v138, s[56:57]
	s_add_u32 s56, s56, 0x1e8000
	s_addc_u32 s57, s57, 0
	global_load_dwordx4 v[54:57], v138, s[56:57]
	s_add_u32 s56, s56, 0x8000
	s_addc_u32 s57, s57, 0
	global_load_dwordx4 v[58:61], v138, s[56:57]
	s_add_u32 s56, s56, 0x8000
	s_addc_u32 s57, s57, 0
	global_load_dwordx4 v[62:65], v138, s[56:57]
	s_add_u32 s56, s56, 0x8000
	s_addc_u32 s57, s57, 0
	global_load_dwordx4 v[66:69], v138, s[56:57]
	s_add_u32 s56, s56, 0x1e8000
	s_addc_u32 s57, s57, 0
	global_load_dwordx4 v[70:73], v138, s[56:57]
	s_add_u32 s56, s56, 0x8000
	s_addc_u32 s57, s57, 0
	global_load_dwordx4 v[74:77], v138, s[56:57]
	s_add_u32 s56, s56, 0x8000
	s_addc_u32 s57, s57, 0
	global_load_dwordx4 v[78:81], v138, s[56:57]
	s_add_u32 s56, s56, 0x8000
	s_addc_u32 s57, s57, 0
	global_load_dwordx4 v[82:85], v138, s[56:57]
	s_add_u32 s56, s56, 0x1e8000
	s_addc_u32 s57, s57, 0
	global_load_dwordx4 v[86:89], v138, s[56:57]
	s_add_u32 s56, s56, 0x8000
	s_addc_u32 s57, s57, 0
	global_load_dwordx4 v[90:93], v138, s[56:57]
	s_add_u32 s56, s56, 0x8000
	s_addc_u32 s57, s57, 0
	global_load_dwordx4 v[94:97], v138, s[56:57]
	s_add_u32 s56, s56, 0x8000
	s_addc_u32 s57, s57, 0
	global_load_dwordx4 v[98:101], v138, s[56:57]
	s_add_u32 s56, s56, 0x1e8000
	s_addc_u32 s57, s57, 0
	global_load_dwordx4 v[102:105], v138, s[56:57]
	s_add_u32 s56, s56, 0x8000
	s_addc_u32 s57, s57, 0
	global_load_dwordx4 v[106:109], v138, s[56:57]
	s_add_u32 s56, s56, 0x8000
	s_addc_u32 s57, s57, 0
	global_load_dwordx4 v[110:113], v138, s[56:57]
	s_add_u32 s56, s56, 0x8000
	s_addc_u32 s57, s57, 0
	global_load_dwordx4 v[114:117], v138, s[56:57]
	s_add_u32 s56, s56, 0x1e8000
	s_addc_u32 s57, s57, 0
	global_load_dwordx4 v[118:121], v138, s[56:57]
	s_add_u32 s56, s56, 0x8000
	s_addc_u32 s57, s57, 0
	global_load_dwordx4 v[122:125], v138, s[56:57]
	s_add_u32 s56, s56, 0x8000
	s_addc_u32 s57, s57, 0
	global_load_dwordx4 v[126:129], v138, s[56:57]
	s_add_u32 s56, s56, 0x8000
	s_addc_u32 s57, s57, 0
	global_load_dwordx4 v[130:133], v138, s[56:57]

.LBB0_104:
	s_andn2_b64 vcc, exec, s[0:1]
	s_branch .LBB0_106
.LBB0_106:
	s_mov_b64 s[0:1], 0
.LBB0_107:
	s_andn2_b64 vcc, exec, s[0:1]
	s_branch .LBB0_109
.LBB0_109:
	s_mov_b64 s[0:1], 0
.LBB0_110:
	s_andn2_b64 vcc, exec, s[0:1]
	s_branch .LBB0_112
.LBB0_112:
	s_mov_b64 s[0:1], 0
.LBB0_113:
	s_andn2_b64 vcc, exec, s[0:1]
	s_branch .LBB0_90
.LBB0_115:
	v_readlane_b32 s36, v254, 11
	s_mov_b32 s90, s14
	s_cmpk_gt_i32 s14, 0x21ff
	v_readlane_b32 s89, v254, 20
	v_readlane_b32 s95, v254, 22
	v_readlane_b32 s37, v254, 12
	s_cbranch_scc1 .LBB0_143
	v_mbcnt_lo_u32_b32 v0, -1, 0
	v_mbcnt_hi_u32_b32 v0, -1, v0
	v_and_b32_e32 v2, 64, v0
	v_xor_b32_e32 v1, 16, v0
	v_add_u32_e32 v2, 64, v2
	v_cmp_lt_i32_e32 vcc, v1, v2
	v_lshlrev_b32_e32 v64, 3, v134
	s_ashr_i32 s91, s90, 31
	v_cndmask_b32_e32 v1, v0, v1, vcc
	v_ashrrev_i32_e32 v65, 31, v64
	v_lshlrev_b32_e32 v70, 2, v1
	v_xor_b32_e32 v1, 32, v0
	s_lshl_b64 s[2:3], s[90:91], 12
	s_ashr_i32 s43, s42, 31
	v_cmp_lt_i32_e32 vcc, v1, v2
	v_lshl_add_u64 v[66:67], s[2:3], 0, v[64:65]
	s_lshl_b64 s[12:13], s[42:43], 12
	s_lshl_b64 s[2:3], s[90:91], 2
	v_cndmask_b32_e32 v0, v0, v1, vcc
	s_add_u32 s2, s2, 0xa0000
	s_mov_b32 s11, 0
	v_lshlrev_b32_e32 v71, 2, v0
	v_cmp_eq_u32_e64 s[0:1], 0, v134
	v_readlane_b32 s89, v254, 20
	s_addc_u32 s3, s3, 0
	s_lshl_b64 s[16:17], s[42:43], 2
	v_mov_b32_e32 v72, 0
	s_mov_b32 s6, 0x42fe0000
	s_mov_b32 s7, 0x40c0c00
	s_mov_b32 s14, s90
	s_branch .LBB0_118

.LBB0_486:
.LBB0_487:
	v_readlane_b32 s20, v254, 7
	v_readlane_b32 s21, v254, 8
	s_cmp_gt_i32 s21, 4
	v_readlane_b32 s22, v254, 9
	v_readlane_b32 s23, v254, 10
	s_cbranch_scc0 .LBB0_543
	v_readlane_b32 s0, v255, 5
	v_readlane_b32 s1, v255, 6
	s_andn2_b64 vcc, exec, s[0:1]
	s_mov_b64 s[4:5], 0
	s_cbranch_vccnz .LBB0_490
	s_waitcnt vmcnt(31)
	v_mbcnt_lo_u32_b32 v0, -1, 0
	v_mbcnt_hi_u32_b32 v0, -1, v0
	s_nop 0
	v_cmp_eq_u32_e32 vcc, 0, v0
	s_and_b64 s[4:5], vcc, exec

.LBB0_852:
.LBB0_855:
.LBB0_857:
.LBB0_859:
.LBB0_860:
.LBB0_863:
.LBB0_865:
.LBB0_867:
.LBB0_868:
.LBB0_871:
.LBB0_873:
.LBB0_875:
.LBB0_876:
.LBB0_879:
.LBB0_881:
.LBB0_883:
.LBB0_884:
	s_or_b64 exec, exec, s[4:5]
	v_readlane_b32 s20, v254, 7
	v_readlane_b32 s21, v254, 8
	s_cmp_gt_i32 s21, 6
	v_readlane_b32 s22, v254, 9
	v_readlane_b32 s23, v254, 10
	s_cbranch_scc0 .LBB0_940
	v_readlane_b32 s0, v255, 5
	v_readlane_b32 s1, v255, 6
	s_andn2_b64 vcc, exec, s[0:1]
	s_mov_b64 s[4:5], 0
	s_cbranch_vccnz .LBB0_887
	v_mbcnt_lo_u32_b32 v0, -1, 0
	v_mbcnt_hi_u32_b32 v0, -1, v0
	s_nop 0
	v_cmp_eq_u32_e32 vcc, 0, v0
	s_and_b64 s[4:5], vcc, exec
